# adds hand-written relu^2 epilogue path for the up-projection GEMM and a peeled first K-iteration per tile whose first two vmcnt waits skip over the previous tile's epilogue stores
# speedup vs baseline: 1.0129x; 1.0088x over previous
.LBB0_169:
	v_readlane_b32 s2, v247, 52
	s_add_u32 s37, s2, s0
	v_readlane_b32 s0, v247, 53
	s_addc_u32 s39, s0, s1
	s_add_i32 m0, s31, 0x18000
	v_lshl_add_u64 v[0:1], v[0:1], 0, s[82:83]
	s_waitcnt vmcnt(2)
	s_barrier
	global_load_lds_dwordx4 v[0:1], off
	v_lshl_add_u64 v[0:1], v[2:3], 0, s[82:83]
	s_add_i32 m0, s31, 0x1a000
	s_add_i32 s47, s31, 0x8000
	global_load_lds_dwordx4 v[0:1], off
	v_lshl_add_u64 v[0:1], v[8:9], 0, s[82:83]
	s_mov_b32 m0, s47
	s_add_i32 s50, s31, 0xa000
	global_load_lds_dwordx4 v[0:1], off
	v_lshl_add_u64 v[0:1], v[10:11], 0, s[82:83]
	s_mov_b32 m0, s50
	v_bfe_u32 v18, v182, 4, 2
	global_load_lds_dwordx4 v[0:1], off
	s_add_i32 m0, s31, 0x1c000
	v_lshl_add_u64 v[0:1], v[4:5], 0, s[82:83]
	global_load_lds_dwordx4 v[0:1], off
	v_lshl_add_u64 v[0:1], v[6:7], 0, s[82:83]
	s_add_i32 m0, s31, 0x1e000
	v_and_b32_e32 v19, 15, v182
	global_load_lds_dwordx4 v[0:1], off
	v_lshlrev_b32_e32 v20, 4, v18
	v_lshl_or_b32 v183, s4, 6, v19
	v_lshl_or_b32 v19, v19, 6, v20
	v_lshlrev_b32_e32 v20, 2, v182
	s_lshl_b32 s0, s4, 13
	v_and_b32_e32 v20, 32, v20
	v_bitop3_b32 v21, v19, s0, v20 bitop3:0xde
	s_lshl_b32 s0, s5, 5
	v_add_u32_e32 v0, v17, v15
	s_lshr_b32 s46, s19, 6
	s_and_b32 s0, s0, 0x60
	v_add_lshl_u32 v0, v0, v16, 1
	v_mov_b32_e32 v1, v175
	s_lshl_b32 s1, s0, 7
	s_waitcnt vmcnt(6)
	s_add_i32 s51, s46, -2
	v_lshl_add_u64 v[186:187], s[78:79], 0, v[0:1]
	v_add_u32_e32 v0, v14, v12
	s_cmpk_lt_u32 s18, 0x100
	v_add_lshl_u32 v0, v0, v13, 1
	s_sext_i32_i8 s56, s20
	v_bitop3_b32 v192, s1, v19, v20 bitop3:0xf6
	s_cselect_b64 s[18:19], -1, 0
	s_and_b32 s73, s73, 0xffff
	v_lshl_or_b32 v193, v18, 2, s0
	v_lshl_add_u64 v[188:189], s[78:79], 0, v[0:1]
	s_mov_b32 s52, 0
	v_add_u32_e32 v194, 0, v21
	s_barrier
	s_mov_b32 s53, 0
	v_writelane_b32 v246, s53, 43
	s_branch .LBB0_172

.LBB0_182:
	s_add_u32 s57, s22, 0x100
	s_addc_u32 s59, s23, 0
	s_add_u32 s22, s24, 0x80
	v_mov_b32_e32 v0, 0
	s_addc_u32 s23, s25, 0
	s_mov_b32 s24, 0
	v_mov_b32_e32 v1, v0
	v_mov_b32_e32 v2, v0
	v_mov_b32_e32 v3, v0
	v_mov_b32_e32 v4, v0
	v_mov_b32_e32 v5, v0
	v_mov_b32_e32 v6, v0
	v_mov_b32_e32 v7, v0
	v_mov_b32_e32 v8, v0
	v_mov_b32_e32 v9, v0
	v_mov_b32_e32 v10, v0
	v_mov_b32_e32 v11, v0
	v_mov_b32_e32 v16, v0
	v_mov_b32_e32 v17, v0
	v_mov_b32_e32 v18, v0
	v_mov_b32_e32 v19, v0
	v_mov_b32_e32 v24, v0
	v_mov_b32_e32 v25, v0
	v_mov_b32_e32 v26, v0
	v_mov_b32_e32 v27, v0
	v_mov_b32_e32 v32, v0
	v_mov_b32_e32 v33, v0
	v_mov_b32_e32 v34, v0
	v_mov_b32_e32 v35, v0
	v_mov_b32_e32 v48, v0
	v_mov_b32_e32 v49, v0
	v_mov_b32_e32 v50, v0
	v_mov_b32_e32 v51, v0
	v_mov_b32_e32 v52, v0
	v_mov_b32_e32 v53, v0
	v_mov_b32_e32 v54, v0
	v_mov_b32_e32 v55, v0
	v_mov_b32_e32 v12, v0
	v_mov_b32_e32 v13, v0
	v_mov_b32_e32 v14, v0
	v_mov_b32_e32 v15, v0
	v_mov_b32_e32 v20, v0
	v_mov_b32_e32 v21, v0
	v_mov_b32_e32 v22, v0
	v_mov_b32_e32 v23, v0
	v_mov_b32_e32 v28, v0
	v_mov_b32_e32 v29, v0
	v_mov_b32_e32 v30, v0
	v_mov_b32_e32 v31, v0
	v_mov_b32_e32 v36, v0
	v_mov_b32_e32 v37, v0
	v_mov_b32_e32 v38, v0
	v_mov_b32_e32 v39, v0
	v_mov_b32_e32 v40, v0
	v_mov_b32_e32 v41, v0
	v_mov_b32_e32 v42, v0
	v_mov_b32_e32 v43, v0
	v_mov_b32_e32 v44, v0
	v_mov_b32_e32 v45, v0
	v_mov_b32_e32 v46, v0
	v_mov_b32_e32 v47, v0
	v_mov_b32_e32 v56, v0
	v_mov_b32_e32 v57, v0
	v_mov_b32_e32 v58, v0
	v_mov_b32_e32 v59, v0
	v_mov_b32_e32 v60, v0
	v_mov_b32_e32 v61, v0
	v_mov_b32_e32 v62, v0
	v_mov_b32_e32 v63, v0
	v_mov_b32_e32 v64, v0
	v_mov_b32_e32 v65, v0
	v_mov_b32_e32 v66, v0
	v_mov_b32_e32 v67, v0
	v_mov_b32_e32 v68, v0
	v_mov_b32_e32 v69, v0
	v_mov_b32_e32 v70, v0
	v_mov_b32_e32 v71, v0
	v_mov_b32_e32 v72, v0
	v_mov_b32_e32 v73, v0
	v_mov_b32_e32 v74, v0
	v_mov_b32_e32 v75, v0
	v_mov_b32_e32 v84, v0
	v_mov_b32_e32 v85, v0
	v_mov_b32_e32 v86, v0
	v_mov_b32_e32 v87, v0
	v_mov_b32_e32 v96, v0
	v_mov_b32_e32 v97, v0
	v_mov_b32_e32 v98, v0
	v_mov_b32_e32 v99, v0
	v_mov_b32_e32 v100, v0
	v_mov_b32_e32 v101, v0
	v_mov_b32_e32 v102, v0
	v_mov_b32_e32 v103, v0
	v_mov_b32_e32 v128, v0
	v_mov_b32_e32 v129, v0
	v_mov_b32_e32 v130, v0
	v_mov_b32_e32 v131, v0
	v_mov_b32_e32 v132, v0
	v_mov_b32_e32 v133, v0
	v_mov_b32_e32 v134, v0
	v_mov_b32_e32 v135, v0
	v_mov_b32_e32 v76, v0
	v_mov_b32_e32 v77, v0
	v_mov_b32_e32 v78, v0
	v_mov_b32_e32 v79, v0
	v_mov_b32_e32 v80, v0
	v_mov_b32_e32 v81, v0
	v_mov_b32_e32 v82, v0
	v_mov_b32_e32 v83, v0
	v_mov_b32_e32 v88, v0
	v_mov_b32_e32 v89, v0
	v_mov_b32_e32 v90, v0
	v_mov_b32_e32 v91, v0
	v_mov_b32_e32 v92, v0
	v_mov_b32_e32 v93, v0
	v_mov_b32_e32 v94, v0
	v_mov_b32_e32 v95, v0
	v_mov_b32_e32 v120, v0
	v_mov_b32_e32 v121, v0
	v_mov_b32_e32 v122, v0
	v_mov_b32_e32 v123, v0
	v_mov_b32_e32 v124, v0
	v_mov_b32_e32 v125, v0
	v_mov_b32_e32 v126, v0
	v_mov_b32_e32 v127, v0
	v_mov_b32_e32 v136, v0
	v_mov_b32_e32 v137, v0
	v_mov_b32_e32 v138, v0
	v_mov_b32_e32 v139, v0
	v_mov_b32_e32 v140, v0
	v_mov_b32_e32 v141, v0
	v_mov_b32_e32 v142, v0
	v_mov_b32_e32 v143, v0
	v_readlane_b32 s2, v246, 43
	s_cmp_eq_u32 s2, 0
	s_cbranch_scc1 .LBB0_183
	s_add_i32 s60, s24, 2
	s_add_u32 s2, s22, 0x80
	s_addc_u32 s3, s23, 0
	s_add_i32 s61, 0, 0x10000
	s_cmp_eq_u32 s51, s24
	s_cselect_b32 s25, s1, s3
	s_cselect_b32 s24, s0, s2
	s_cselect_b32 s3, s21, s59
	s_cselect_b32 s2, s20, s57
	s_add_i32 s62, 0, 0x14000
	v_add_u32_e32 v116, s61, v192
	v_add_u32_e32 v156, s62, v192
	ds_read_b128 v[104:107], v116
	ds_read_b128 v[108:111], v116 offset:1024
	ds_read_b128 v[112:115], v116 offset:2048
	ds_read_b128 v[116:119], v116 offset:3072
	ds_read_b128 v[144:147], v156
	ds_read_b128 v[148:151], v156 offset:1024
	ds_read_b128 v[152:155], v156 offset:2048
	ds_read_b128 v[156:159], v156 offset:3072
	v_lshl_add_u64 v[190:191], s[22:23], 0, v[188:189]
	s_add_i32 m0, s31, 0xc000
	ds_read_b128 v[160:163], v194
	ds_read_b128 v[164:167], v194 offset:1024
	ds_read_b128 v[196:199], v194 offset:2048
	ds_read_b128 v[200:203], v194 offset:3072
	ds_read_b128 v[210:213], v194 offset:4096
	ds_read_b128 v[214:217], v194 offset:5120
	ds_read_b128 v[218:221], v194 offset:6144
	ds_read_b128 v[222:225], v194 offset:7168
	global_load_lds_dwordx4 v[190:191], off
	v_lshl_add_u64 v[190:191], s[22:23], 0, v[186:187]
	s_add_i32 m0, s31, 0xe000
	s_nop 0
	global_load_lds_dwordx4 v[190:191], off
	s_waitcnt vmcnt(40)
	s_waitcnt lgkmcnt(0)
	s_barrier
	s_setprio 1
	s_waitcnt lgkmcnt(0)
	v_mfma_f32_16x16x32_bf16 v[140:143], v[104:107], v[160:163], v[140:143]
	v_mfma_f32_16x16x32_bf16 v[140:143], v[108:111], v[164:167], v[140:143]
	v_mfma_f32_16x16x32_bf16 v[136:139], v[112:115], v[160:163], v[136:139]
	v_mfma_f32_16x16x32_bf16 v[136:139], v[116:119], v[164:167], v[136:139]
	v_mfma_f32_16x16x32_bf16 v[124:127], v[104:107], v[196:199], v[124:127]
	v_mfma_f32_16x16x32_bf16 v[124:127], v[108:111], v[200:203], v[124:127]
	v_mfma_f32_16x16x32_bf16 v[120:123], v[112:115], v[196:199], v[120:123]
	v_mfma_f32_16x16x32_bf16 v[120:123], v[116:119], v[200:203], v[120:123]
	v_mfma_f32_16x16x32_bf16 v[92:95], v[104:107], v[210:213], v[92:95]
	v_mfma_f32_16x16x32_bf16 v[92:95], v[108:111], v[214:217], v[92:95]
	v_mfma_f32_16x16x32_bf16 v[88:91], v[112:115], v[210:213], v[88:91]
	v_mfma_f32_16x16x32_bf16 v[88:91], v[116:119], v[214:217], v[88:91]
	v_mfma_f32_16x16x32_bf16 v[80:83], v[104:107], v[218:221], v[80:83]
	v_mfma_f32_16x16x32_bf16 v[80:83], v[108:111], v[222:225], v[80:83]
	v_mfma_f32_16x16x32_bf16 v[76:79], v[112:115], v[218:221], v[76:79]
	v_mfma_f32_16x16x32_bf16 v[76:79], v[116:119], v[222:225], v[76:79]
	s_setprio 0
	s_setprio 1
	v_mfma_f32_16x16x32_bf16 v[132:135], v[144:147], v[160:163], v[132:135]
	v_mfma_f32_16x16x32_bf16 v[132:135], v[148:151], v[164:167], v[132:135]
	v_mfma_f32_16x16x32_bf16 v[128:131], v[152:155], v[160:163], v[128:131]
	v_mfma_f32_16x16x32_bf16 v[128:131], v[156:159], v[164:167], v[128:131]
	v_mfma_f32_16x16x32_bf16 v[100:103], v[144:147], v[196:199], v[100:103]
	v_mfma_f32_16x16x32_bf16 v[100:103], v[148:151], v[200:203], v[100:103]
	v_mfma_f32_16x16x32_bf16 v[96:99], v[152:155], v[196:199], v[96:99]
	v_mfma_f32_16x16x32_bf16 v[96:99], v[156:159], v[200:203], v[96:99]
	v_mfma_f32_16x16x32_bf16 v[84:87], v[144:147], v[210:213], v[84:87]
	v_mfma_f32_16x16x32_bf16 v[84:87], v[148:151], v[214:217], v[84:87]
	v_mfma_f32_16x16x32_bf16 v[72:75], v[152:155], v[210:213], v[72:75]
	v_mfma_f32_16x16x32_bf16 v[72:75], v[156:159], v[214:217], v[72:75]
	v_mfma_f32_16x16x32_bf16 v[68:71], v[144:147], v[218:221], v[68:71]
	v_mfma_f32_16x16x32_bf16 v[68:71], v[148:151], v[222:225], v[68:71]
	v_mfma_f32_16x16x32_bf16 v[64:67], v[152:155], v[218:221], v[64:67]
	v_mfma_f32_16x16x32_bf16 v[64:67], v[156:159], v[222:225], v[64:67]
	s_setprio 0
	s_barrier
	s_add_i32 s61, s61, s30
	v_lshl_add_u64 v[190:191], s[2:3], 0, v[174:175]
	s_mov_b32 m0, s61
	ds_read_b128 v[160:163], v194 offset:16384
	ds_read_b128 v[164:167], v194 offset:17408
	ds_read_b128 v[196:199], v194 offset:18432
	ds_read_b128 v[200:203], v194 offset:19456
	ds_read_b128 v[210:213], v194 offset:20480
	ds_read_b128 v[214:217], v194 offset:21504
	ds_read_b128 v[218:221], v194 offset:22528
	ds_read_b128 v[222:225], v194 offset:23552
	global_load_lds_dwordx4 v[190:191], off
	s_add_i32 m0, s61, 0x2000
	v_lshl_add_u64 v[226:227], s[2:3], 0, v[184:185]
	s_add_u32 s2, s2, s27
	s_addc_u32 s3, s3, 0
	s_add_i32 s61, s62, s30
	global_load_lds_dwordx4 v[226:227], off
	v_lshl_add_u64 v[228:229], s[2:3], 0, v[174:175]
	s_mov_b32 m0, s61
	v_lshl_add_u64 v[230:231], s[2:3], 0, v[184:185]
	global_load_lds_dwordx4 v[228:229], off
	s_add_i32 m0, s61, 0x2000
	v_lshl_add_u64 v[232:233], s[24:25], 0, v[168:169]
	global_load_lds_dwordx4 v[230:231], off
	s_mov_b32 m0, s31
	v_lshl_add_u64 v[234:235], s[24:25], 0, v[170:171]
	global_load_lds_dwordx4 v[232:233], off
	s_mov_b32 m0, s34
	s_nop 0
	global_load_lds_dwordx4 v[234:235], off
	s_waitcnt vmcnt(40)
	s_waitcnt lgkmcnt(0)
	s_barrier
	s_setprio 1
	s_waitcnt lgkmcnt(0)
	v_mfma_f32_16x16x32_bf16 v[60:63], v[104:107], v[160:163], v[60:63]
	v_mfma_f32_16x16x32_bf16 v[60:63], v[108:111], v[164:167], v[60:63]
	v_mfma_f32_16x16x32_bf16 v[56:59], v[112:115], v[160:163], v[56:59]
	v_mfma_f32_16x16x32_bf16 v[56:59], v[116:119], v[164:167], v[56:59]
	v_mfma_f32_16x16x32_bf16 v[44:47], v[104:107], v[196:199], v[44:47]
	v_mfma_f32_16x16x32_bf16 v[44:47], v[108:111], v[200:203], v[44:47]
	v_mfma_f32_16x16x32_bf16 v[40:43], v[112:115], v[196:199], v[40:43]
	v_mfma_f32_16x16x32_bf16 v[40:43], v[116:119], v[200:203], v[40:43]
	v_mfma_f32_16x16x32_bf16 v[36:39], v[104:107], v[210:213], v[36:39]
	v_mfma_f32_16x16x32_bf16 v[36:39], v[108:111], v[214:217], v[36:39]
	v_mfma_f32_16x16x32_bf16 v[28:31], v[112:115], v[210:213], v[28:31]
	v_mfma_f32_16x16x32_bf16 v[28:31], v[116:119], v[214:217], v[28:31]
	v_mfma_f32_16x16x32_bf16 v[20:23], v[104:107], v[218:221], v[20:23]
	v_mfma_f32_16x16x32_bf16 v[20:23], v[108:111], v[222:225], v[20:23]
	v_mfma_f32_16x16x32_bf16 v[12:15], v[112:115], v[218:221], v[12:15]
	v_mfma_f32_16x16x32_bf16 v[12:15], v[116:119], v[222:225], v[12:15]
	s_setprio 0
	s_setprio 1
	v_mfma_f32_16x16x32_bf16 v[52:55], v[144:147], v[160:163], v[52:55]
	v_mfma_f32_16x16x32_bf16 v[52:55], v[148:151], v[164:167], v[52:55]
	v_mfma_f32_16x16x32_bf16 v[48:51], v[152:155], v[160:163], v[48:51]
	v_mfma_f32_16x16x32_bf16 v[48:51], v[156:159], v[164:167], v[48:51]
	v_mfma_f32_16x16x32_bf16 v[32:35], v[144:147], v[196:199], v[32:35]
	v_mfma_f32_16x16x32_bf16 v[32:35], v[148:151], v[200:203], v[32:35]
	v_mfma_f32_16x16x32_bf16 v[24:27], v[152:155], v[196:199], v[24:27]
	v_mfma_f32_16x16x32_bf16 v[24:27], v[156:159], v[200:203], v[24:27]
	v_mfma_f32_16x16x32_bf16 v[16:19], v[144:147], v[210:213], v[16:19]
	v_mfma_f32_16x16x32_bf16 v[16:19], v[148:151], v[214:217], v[16:19]
	v_mfma_f32_16x16x32_bf16 v[8:11], v[152:155], v[210:213], v[8:11]
	v_mfma_f32_16x16x32_bf16 v[8:11], v[156:159], v[214:217], v[8:11]
	v_mfma_f32_16x16x32_bf16 v[4:7], v[144:147], v[218:221], v[4:7]
	v_mfma_f32_16x16x32_bf16 v[4:7], v[148:151], v[222:225], v[4:7]
	v_mfma_f32_16x16x32_bf16 v[0:3], v[152:155], v[218:221], v[0:3]
	v_mfma_f32_16x16x32_bf16 v[0:3], v[156:159], v[222:225], v[0:3]
	s_setprio 0
	s_barrier
	s_add_i32 s61, 0, 0x18000
	s_add_i32 s62, 0, 0x1c000
	v_add_u32_e32 v116, s61, v192
	v_add_u32_e32 v156, s62, v192
	ds_read_b128 v[104:107], v116
	ds_read_b128 v[108:111], v116 offset:1024
	ds_read_b128 v[112:115], v116 offset:2048
	ds_read_b128 v[116:119], v116 offset:3072
	ds_read_b128 v[144:147], v156
	ds_read_b128 v[148:151], v156 offset:1024
	ds_read_b128 v[152:155], v156 offset:2048
	ds_read_b128 v[156:159], v156 offset:3072
	s_add_u32 s2, s24, s78
	s_addc_u32 s3, s25, 0
	s_mov_b32 m0, s35
	v_lshl_add_u64 v[236:237], s[2:3], 0, v[168:169]
	ds_read_b128 v[160:163], v194 offset:32768
	ds_read_b128 v[164:167], v194 offset:33792
	ds_read_b128 v[196:199], v194 offset:34816
	ds_read_b128 v[200:203], v194 offset:35840
	ds_read_b128 v[210:213], v194 offset:36864
	ds_read_b128 v[214:217], v194 offset:37888
	ds_read_b128 v[218:221], v194 offset:38912
	ds_read_b128 v[222:225], v194 offset:39936
	global_load_lds_dwordx4 v[236:237], off
	v_lshl_add_u64 v[236:237], s[2:3], 0, v[170:171]
	s_mov_b32 m0, s36
	s_nop 0
	global_load_lds_dwordx4 v[236:237], off
	s_waitcnt vmcnt(8)
	s_waitcnt lgkmcnt(0)
	s_barrier
	s_setprio 1
	s_waitcnt lgkmcnt(0)
	v_mfma_f32_16x16x32_bf16 v[140:143], v[104:107], v[160:163], v[140:143]
	v_mfma_f32_16x16x32_bf16 v[140:143], v[108:111], v[164:167], v[140:143]
	v_mfma_f32_16x16x32_bf16 v[136:139], v[112:115], v[160:163], v[136:139]
	v_mfma_f32_16x16x32_bf16 v[136:139], v[116:119], v[164:167], v[136:139]
	v_mfma_f32_16x16x32_bf16 v[124:127], v[104:107], v[196:199], v[124:127]
	v_mfma_f32_16x16x32_bf16 v[124:127], v[108:111], v[200:203], v[124:127]
	v_mfma_f32_16x16x32_bf16 v[120:123], v[112:115], v[196:199], v[120:123]
	v_mfma_f32_16x16x32_bf16 v[120:123], v[116:119], v[200:203], v[120:123]
	v_mfma_f32_16x16x32_bf16 v[92:95], v[104:107], v[210:213], v[92:95]
	v_mfma_f32_16x16x32_bf16 v[92:95], v[108:111], v[214:217], v[92:95]
	v_mfma_f32_16x16x32_bf16 v[88:91], v[112:115], v[210:213], v[88:91]
	v_mfma_f32_16x16x32_bf16 v[88:91], v[116:119], v[214:217], v[88:91]
	v_mfma_f32_16x16x32_bf16 v[80:83], v[104:107], v[218:221], v[80:83]
	v_mfma_f32_16x16x32_bf16 v[80:83], v[108:111], v[222:225], v[80:83]
	v_mfma_f32_16x16x32_bf16 v[76:79], v[112:115], v[218:221], v[76:79]
	v_mfma_f32_16x16x32_bf16 v[76:79], v[116:119], v[222:225], v[76:79]
	s_setprio 0
	s_setprio 1
	v_mfma_f32_16x16x32_bf16 v[132:135], v[144:147], v[160:163], v[132:135]
	v_mfma_f32_16x16x32_bf16 v[132:135], v[148:151], v[164:167], v[132:135]
	v_mfma_f32_16x16x32_bf16 v[128:131], v[152:155], v[160:163], v[128:131]
	v_mfma_f32_16x16x32_bf16 v[128:131], v[156:159], v[164:167], v[128:131]
	v_mfma_f32_16x16x32_bf16 v[100:103], v[144:147], v[196:199], v[100:103]
	v_mfma_f32_16x16x32_bf16 v[100:103], v[148:151], v[200:203], v[100:103]
	v_mfma_f32_16x16x32_bf16 v[96:99], v[152:155], v[196:199], v[96:99]
	v_mfma_f32_16x16x32_bf16 v[96:99], v[156:159], v[200:203], v[96:99]
	v_mfma_f32_16x16x32_bf16 v[84:87], v[144:147], v[210:213], v[84:87]
	v_mfma_f32_16x16x32_bf16 v[84:87], v[148:151], v[214:217], v[84:87]
	v_mfma_f32_16x16x32_bf16 v[72:75], v[152:155], v[210:213], v[72:75]
	v_mfma_f32_16x16x32_bf16 v[72:75], v[156:159], v[214:217], v[72:75]
	v_mfma_f32_16x16x32_bf16 v[68:71], v[144:147], v[218:221], v[68:71]
	v_mfma_f32_16x16x32_bf16 v[68:71], v[148:151], v[222:225], v[68:71]
	v_mfma_f32_16x16x32_bf16 v[64:67], v[152:155], v[218:221], v[64:67]
	v_mfma_f32_16x16x32_bf16 v[64:67], v[156:159], v[222:225], v[64:67]
	s_setprio 0
	s_barrier
	s_add_i32 s2, s61, s30
	v_lshl_add_u64 v[190:191], v[190:191], 0, s[82:83]
	s_mov_b32 m0, s2
	ds_read_b128 v[160:163], v194 offset:49152
	ds_read_b128 v[164:167], v194 offset:50176
	ds_read_b128 v[196:199], v194 offset:51200
	ds_read_b128 v[200:203], v194 offset:52224
	ds_read_b128 v[210:213], v194 offset:53248
	ds_read_b128 v[214:217], v194 offset:54272
	ds_read_b128 v[218:221], v194 offset:55296
	ds_read_b128 v[222:225], v194 offset:56320
	global_load_lds_dwordx4 v[190:191], off
	v_lshl_add_u64 v[190:191], v[226:227], 0, s[82:83]
	s_add_i32 m0, s2, 0x2000
	s_add_i32 s2, s62, s30
	global_load_lds_dwordx4 v[190:191], off
	v_lshl_add_u64 v[190:191], v[228:229], 0, s[82:83]
	s_mov_b32 m0, s2
	s_nop 0
	global_load_lds_dwordx4 v[190:191], off
	v_lshl_add_u64 v[190:191], v[230:231], 0, s[82:83]
	s_add_i32 m0, s2, 0x2000
	s_nop 0
	global_load_lds_dwordx4 v[190:191], off
	v_lshl_add_u64 v[190:191], v[232:233], 0, s[82:83]
	s_mov_b32 m0, s47
	s_nop 0
	global_load_lds_dwordx4 v[190:191], off
	v_lshl_add_u64 v[190:191], v[234:235], 0, s[82:83]
	s_mov_b32 m0, s50
	s_nop 0
	global_load_lds_dwordx4 v[190:191], off
	s_waitcnt vmcnt(8)
	s_waitcnt lgkmcnt(0)
	s_barrier
	s_setprio 1
	s_waitcnt lgkmcnt(0)
	v_mfma_f32_16x16x32_bf16 v[60:63], v[104:107], v[160:163], v[60:63]
	v_mfma_f32_16x16x32_bf16 v[60:63], v[108:111], v[164:167], v[60:63]
	v_mfma_f32_16x16x32_bf16 v[56:59], v[112:115], v[160:163], v[56:59]
	v_mfma_f32_16x16x32_bf16 v[56:59], v[116:119], v[164:167], v[56:59]
	v_mfma_f32_16x16x32_bf16 v[44:47], v[104:107], v[196:199], v[44:47]
	v_mfma_f32_16x16x32_bf16 v[44:47], v[108:111], v[200:203], v[44:47]
	v_mfma_f32_16x16x32_bf16 v[40:43], v[112:115], v[196:199], v[40:43]
	v_mfma_f32_16x16x32_bf16 v[40:43], v[116:119], v[200:203], v[40:43]
	v_mfma_f32_16x16x32_bf16 v[36:39], v[104:107], v[210:213], v[36:39]
	v_mfma_f32_16x16x32_bf16 v[36:39], v[108:111], v[214:217], v[36:39]
	v_mfma_f32_16x16x32_bf16 v[28:31], v[112:115], v[210:213], v[28:31]
	v_mfma_f32_16x16x32_bf16 v[28:31], v[116:119], v[214:217], v[28:31]
	v_mfma_f32_16x16x32_bf16 v[20:23], v[104:107], v[218:221], v[20:23]
	v_mfma_f32_16x16x32_bf16 v[20:23], v[108:111], v[222:225], v[20:23]
	v_mfma_f32_16x16x32_bf16 v[12:15], v[112:115], v[218:221], v[12:15]
	v_mfma_f32_16x16x32_bf16 v[12:15], v[116:119], v[222:225], v[12:15]
	s_setprio 0
	s_setprio 1
	v_mfma_f32_16x16x32_bf16 v[52:55], v[144:147], v[160:163], v[52:55]
	v_mfma_f32_16x16x32_bf16 v[52:55], v[148:151], v[164:167], v[52:55]
	v_mfma_f32_16x16x32_bf16 v[48:51], v[152:155], v[160:163], v[48:51]
	v_mfma_f32_16x16x32_bf16 v[48:51], v[156:159], v[164:167], v[48:51]
	v_mfma_f32_16x16x32_bf16 v[32:35], v[144:147], v[196:199], v[32:35]
	v_mfma_f32_16x16x32_bf16 v[32:35], v[148:151], v[200:203], v[32:35]
	v_mfma_f32_16x16x32_bf16 v[24:27], v[152:155], v[196:199], v[24:27]
	v_mfma_f32_16x16x32_bf16 v[24:27], v[156:159], v[200:203], v[24:27]
	v_mfma_f32_16x16x32_bf16 v[16:19], v[144:147], v[210:213], v[16:19]
	v_mfma_f32_16x16x32_bf16 v[16:19], v[148:151], v[214:217], v[16:19]
	v_mfma_f32_16x16x32_bf16 v[8:11], v[152:155], v[210:213], v[8:11]
	v_mfma_f32_16x16x32_bf16 v[8:11], v[156:159], v[214:217], v[8:11]
	v_mfma_f32_16x16x32_bf16 v[4:7], v[144:147], v[218:221], v[4:7]
	v_mfma_f32_16x16x32_bf16 v[4:7], v[148:151], v[222:225], v[4:7]
	v_mfma_f32_16x16x32_bf16 v[0:3], v[152:155], v[218:221], v[0:3]
	v_mfma_f32_16x16x32_bf16 v[0:3], v[156:159], v[222:225], v[0:3]
	s_setprio 0
	s_barrier
	s_add_u32 s57, s57, 0x100
	s_addc_u32 s59, s59, 0
	s_add_u32 s22, s22, 0x100
	s_addc_u32 s23, s23, 0
	s_cmp_ge_u32 s60, s46
	s_mov_b32 s24, s60
	s_cbranch_scc1 .Lexit_183

.Lexit_183:
	s_and_b64 vcc, exec, s[18:19]
	s_cbranch_vccz .LBB0_186
	s_barrier
.LBB0_186:
	s_mov_b32 s2, 1
	v_writelane_b32 v246, s2, 43
	s_ashr_i32 s2, s55, 4
	v_lshl_or_b32 v242, s56, 8, v193
	s_mul_hi_i32 s3, s2, 0x6000
	s_mulk_i32 s2, 0x6000
	s_add_u32 s2, s37, s2
	v_ashrrev_i32_e32 v243, 31, v242
	s_addc_u32 s3, s39, s3
	v_lshlrev_b64 v[144:145], 2, v[242:243]
	v_lshl_add_u64 v[104:105], s[2:3], 0, v[144:145]
	v_lshl_add_u32 v244, s55, 8, v183
	v_readlane_b32 s2, v247, 56
	v_readlane_b32 s3, v247, 57
	v_ashrrev_i32_e32 v245, 31, v244
	v_lshlrev_b64 v[146:147], 12, v[244:245]
	v_lshl_add_u64 v[144:145], s[2:3], 0, v[144:145]
	v_lshl_add_u64 v[190:191], v[144:145], 0, v[146:147]
	global_load_dwordx4 v[116:119], v[104:105], off
	global_load_dwordx4 v[112:115], v[104:105], off offset:64
	global_load_dwordx4 v[108:111], v[104:105], off offset:512
	s_nop 0
	global_load_dwordx4 v[104:107], v[104:105], off offset:576
	v_lshlrev_b32_e32 v195, 2, v242
	v_lshl_add_u32 v195, v244, 12, v195
	s_mov_b64 s[22:23], -1
	global_load_dwordx4 v[196:199], v[190:191], off
	global_load_dwordx4 v[200:203], v[190:191], off offset:64
	global_load_dwordx4 v[210:213], v[190:191], off offset:512
	global_load_dwordx4 v[214:217], v[190:191], off offset:576
	s_mov_b64 s[2:3], 0x10000
	v_lshl_add_u64 v[244:245], v[190:191], 0, s[2:3]
	global_load_dwordx4 v[218:221], v[244:245], off
	global_load_dwordx4 v[222:225], v[244:245], off offset:64
	global_load_dwordx4 v[226:229], v[244:245], off offset:512
	global_load_dwordx4 v[230:233], v[244:245], off offset:576
	s_mov_b64 s[2:3], 0x20000
	v_lshl_add_u64 v[242:243], v[190:191], 0, s[2:3]
	global_load_dwordx4 v[234:237], v[242:243], off
	global_load_dwordx4 v[238:241], v[242:243], off offset:64
	global_load_dwordx4 v[164:167], v[242:243], off offset:512
	global_load_dwordx4 v[160:163], v[242:243], off offset:576
	s_mov_b64 s[2:3], 0x30000
	v_lshl_add_u64 v[244:245], v[190:191], 0, s[2:3]
	global_load_dwordx4 v[156:159], v[244:245], off
	global_load_dwordx4 v[152:155], v[244:245], off offset:64
	global_load_dwordx4 v[148:151], v[244:245], off offset:512
	global_load_dwordx4 v[144:147], v[244:245], off offset:576
	s_waitcnt vmcnt(12)
	v_pk_fma_f32 v[142:143], v[142:143], v[118:119], v[198:199]
	v_pk_fma_f32 v[140:141], v[140:141], v[116:117], v[196:197]
	v_pk_fma_f32 v[138:139], v[138:139], v[114:115], v[202:203]
	v_pk_fma_f32 v[136:137], v[136:137], v[112:113], v[200:201]
	v_pk_fma_f32 v[134:135], v[134:135], v[110:111], v[212:213]
	v_pk_fma_f32 v[132:133], v[132:133], v[108:109], v[210:211]
	v_pk_fma_f32 v[130:131], v[130:131], v[106:107], v[216:217]
	v_pk_fma_f32 v[128:129], v[128:129], v[104:105], v[214:215]
	buffer_store_dwordx4 v[140:143], v195, s[72:75], 0 offen
	buffer_store_dwordx4 v[136:139], v195, s[72:75], 0 offen offset:64
	buffer_store_dwordx4 v[132:135], v195, s[72:75], 0 offen offset:512
	buffer_store_dwordx4 v[128:131], v195, s[72:75], 0 offen offset:576
	s_mov_b64 s[2:3], 0x80000
	v_lshl_add_u64 v[242:243], v[190:191], 0, s[2:3]
	global_load_dwordx4 v[196:199], v[242:243], off
	global_load_dwordx4 v[200:203], v[242:243], off offset:64
	global_load_dwordx4 v[210:213], v[242:243], off offset:512
	global_load_dwordx4 v[214:217], v[242:243], off offset:576
	s_waitcnt vmcnt(16)
	v_pk_fma_f32 v[126:127], v[126:127], v[118:119], v[220:221]
	v_pk_fma_f32 v[124:125], v[124:125], v[116:117], v[218:219]
	v_pk_fma_f32 v[122:123], v[122:123], v[114:115], v[224:225]
	v_pk_fma_f32 v[120:121], v[120:121], v[112:113], v[222:223]
	v_pk_fma_f32 v[102:103], v[102:103], v[110:111], v[228:229]
	v_pk_fma_f32 v[100:101], v[100:101], v[108:109], v[226:227]
	v_pk_fma_f32 v[98:99], v[98:99], v[106:107], v[232:233]
	v_pk_fma_f32 v[96:97], v[96:97], v[104:105], v[230:231]
	s_mov_b32 s2, 0x10000
	buffer_store_dwordx4 v[124:127], v195, s[72:75], s2 offen
	buffer_store_dwordx4 v[120:123], v195, s[72:75], s2 offen offset:64
	buffer_store_dwordx4 v[100:103], v195, s[72:75], s2 offen offset:512
	buffer_store_dwordx4 v[96:99], v195, s[72:75], s2 offen offset:576
	s_mov_b64 s[2:3], 0x90000
	v_lshl_add_u64 v[244:245], v[190:191], 0, s[2:3]
	global_load_dwordx4 v[218:221], v[244:245], off
	global_load_dwordx4 v[222:225], v[244:245], off offset:64
	global_load_dwordx4 v[226:229], v[244:245], off offset:512
	global_load_dwordx4 v[230:233], v[244:245], off offset:576
	s_waitcnt vmcnt(20)
	v_pk_fma_f32 v[94:95], v[94:95], v[118:119], v[236:237]
	v_pk_fma_f32 v[92:93], v[92:93], v[116:117], v[234:235]
	v_pk_fma_f32 v[90:91], v[90:91], v[114:115], v[240:241]
	v_pk_fma_f32 v[88:89], v[88:89], v[112:113], v[238:239]
	v_pk_fma_f32 v[86:87], v[86:87], v[110:111], v[166:167]
	v_pk_fma_f32 v[84:85], v[84:85], v[108:109], v[164:165]
	v_pk_fma_f32 v[74:75], v[74:75], v[106:107], v[162:163]
	v_pk_fma_f32 v[72:73], v[72:73], v[104:105], v[160:161]
	s_mov_b32 s2, 0x20000
	buffer_store_dwordx4 v[92:95], v195, s[72:75], s2 offen
	buffer_store_dwordx4 v[88:91], v195, s[72:75], s2 offen offset:64
	buffer_store_dwordx4 v[84:87], v195, s[72:75], s2 offen offset:512
	buffer_store_dwordx4 v[72:75], v195, s[72:75], s2 offen offset:576
	s_mov_b64 s[2:3], 0xa0000
	v_lshl_add_u64 v[242:243], v[190:191], 0, s[2:3]
	global_load_dwordx4 v[234:237], v[242:243], off
	global_load_dwordx4 v[238:241], v[242:243], off offset:64
	global_load_dwordx4 v[164:167], v[242:243], off offset:512
	global_load_dwordx4 v[160:163], v[242:243], off offset:576
	s_waitcnt vmcnt(24)
	v_pk_fma_f32 v[82:83], v[82:83], v[118:119], v[158:159]
	v_pk_fma_f32 v[80:81], v[80:81], v[116:117], v[156:157]
	v_pk_fma_f32 v[78:79], v[78:79], v[114:115], v[154:155]
	v_pk_fma_f32 v[76:77], v[76:77], v[112:113], v[152:153]
	v_pk_fma_f32 v[70:71], v[70:71], v[110:111], v[150:151]
	v_pk_fma_f32 v[68:69], v[68:69], v[108:109], v[148:149]
	v_pk_fma_f32 v[66:67], v[66:67], v[106:107], v[146:147]
	v_pk_fma_f32 v[64:65], v[64:65], v[104:105], v[144:145]
	s_mov_b32 s2, 0x30000
	buffer_store_dwordx4 v[80:83], v195, s[72:75], s2 offen
	buffer_store_dwordx4 v[76:79], v195, s[72:75], s2 offen offset:64
	buffer_store_dwordx4 v[68:71], v195, s[72:75], s2 offen offset:512
	buffer_store_dwordx4 v[64:67], v195, s[72:75], s2 offen offset:576
	s_mov_b64 s[2:3], 0xb0000
	v_lshl_add_u64 v[244:245], v[190:191], 0, s[2:3]
	global_load_dwordx4 v[156:159], v[244:245], off
	global_load_dwordx4 v[152:155], v[244:245], off offset:64
	global_load_dwordx4 v[148:151], v[244:245], off offset:512
	global_load_dwordx4 v[144:147], v[244:245], off offset:576
	s_waitcnt vmcnt(24)
	v_pk_fma_f32 v[62:63], v[62:63], v[118:119], v[198:199]
	v_pk_fma_f32 v[60:61], v[60:61], v[116:117], v[196:197]
	v_pk_fma_f32 v[58:59], v[58:59], v[114:115], v[202:203]
	v_pk_fma_f32 v[56:57], v[56:57], v[112:113], v[200:201]
	v_pk_fma_f32 v[54:55], v[54:55], v[110:111], v[212:213]
	v_pk_fma_f32 v[52:53], v[52:53], v[108:109], v[210:211]
	v_pk_fma_f32 v[50:51], v[50:51], v[106:107], v[216:217]
	v_pk_fma_f32 v[48:49], v[48:49], v[104:105], v[214:215]
	s_mov_b32 s2, 0x80000
	buffer_store_dwordx4 v[60:63], v195, s[72:75], s2 offen
	buffer_store_dwordx4 v[56:59], v195, s[72:75], s2 offen offset:64
	buffer_store_dwordx4 v[52:55], v195, s[72:75], s2 offen offset:512
	buffer_store_dwordx4 v[48:51], v195, s[72:75], s2 offen offset:576
	s_waitcnt vmcnt(20)
	v_pk_fma_f32 v[46:47], v[46:47], v[118:119], v[220:221]
	v_pk_fma_f32 v[44:45], v[44:45], v[116:117], v[218:219]
	v_pk_fma_f32 v[42:43], v[42:43], v[114:115], v[224:225]
	v_pk_fma_f32 v[40:41], v[40:41], v[112:113], v[222:223]
	v_pk_fma_f32 v[34:35], v[34:35], v[110:111], v[228:229]
	v_pk_fma_f32 v[32:33], v[32:33], v[108:109], v[226:227]
	v_pk_fma_f32 v[26:27], v[26:27], v[106:107], v[232:233]
	v_pk_fma_f32 v[24:25], v[24:25], v[104:105], v[230:231]
	s_mov_b32 s2, 0x90000
	buffer_store_dwordx4 v[44:47], v195, s[72:75], s2 offen
	buffer_store_dwordx4 v[40:43], v195, s[72:75], s2 offen offset:64
	buffer_store_dwordx4 v[32:35], v195, s[72:75], s2 offen offset:512
	buffer_store_dwordx4 v[24:27], v195, s[72:75], s2 offen offset:576
	s_waitcnt vmcnt(16)
	v_pk_fma_f32 v[38:39], v[38:39], v[118:119], v[236:237]
	v_pk_fma_f32 v[36:37], v[36:37], v[116:117], v[234:235]
	v_pk_fma_f32 v[30:31], v[30:31], v[114:115], v[240:241]
	v_pk_fma_f32 v[28:29], v[28:29], v[112:113], v[238:239]
	v_pk_fma_f32 v[18:19], v[18:19], v[110:111], v[166:167]
	v_pk_fma_f32 v[16:17], v[16:17], v[108:109], v[164:165]
	v_pk_fma_f32 v[10:11], v[10:11], v[106:107], v[162:163]
	v_pk_fma_f32 v[8:9], v[8:9], v[104:105], v[160:161]
	s_mov_b32 s2, 0xa0000
	buffer_store_dwordx4 v[36:39], v195, s[72:75], s2 offen
	buffer_store_dwordx4 v[28:31], v195, s[72:75], s2 offen offset:64
	buffer_store_dwordx4 v[16:19], v195, s[72:75], s2 offen offset:512
	buffer_store_dwordx4 v[8:11], v195, s[72:75], s2 offen offset:576
	s_waitcnt vmcnt(12)
	v_pk_fma_f32 v[22:23], v[22:23], v[118:119], v[158:159]
	v_pk_fma_f32 v[20:21], v[20:21], v[116:117], v[156:157]
	v_pk_fma_f32 v[14:15], v[14:15], v[114:115], v[154:155]
	v_pk_fma_f32 v[12:13], v[12:13], v[112:113], v[152:153]
	v_pk_fma_f32 v[6:7], v[6:7], v[110:111], v[150:151]
	v_pk_fma_f32 v[4:5], v[4:5], v[108:109], v[148:149]
	v_pk_fma_f32 v[2:3], v[2:3], v[106:107], v[146:147]
	v_pk_fma_f32 v[0:1], v[0:1], v[104:105], v[144:145]
	s_mov_b32 s2, 0xb0000
	buffer_store_dwordx4 v[20:23], v195, s[72:75], s2 offen
	buffer_store_dwordx4 v[12:15], v195, s[72:75], s2 offen offset:64
	buffer_store_dwordx4 v[4:7], v195, s[72:75], s2 offen offset:512
	buffer_store_dwordx4 v[0:3], v195, s[72:75], s2 offen offset:576
	s_and_b64 vcc, exec, s[4:5]
	s_cbranch_vccnz .LBB0_171
	s_andn2_b64 vcc, exec, s[16:17]
	s_cbranch_vccnz .LBB0_170
	s_barrier
	s_branch .LBB0_170

.LBB0_232:
	s_cmp_lg_u64 s[48:49], 0
	s_cselect_b64 s[22:23], -1, 0
	s_and_b32 s73, s45, 0xffff
	s_cmp_eq_u32 s89, 1
	s_cselect_b64 s[24:25], -1, 0
	s_cmp_lg_u32 s89, 2
	s_cselect_b64 s[26:27], -1, 0
	s_and_b32 s62, s5, 3
	s_add_i32 m0, s19, 0x18000
	v_lshl_add_u64 v[0:1], v[0:1], 0, s[82:83]
	s_lshl_b32 s2, s4, 13
	s_lshl_b32 s38, s62, 5
	s_waitcnt vmcnt(2)
	s_barrier
	global_load_lds_dwordx4 v[0:1], off
	v_lshl_add_u64 v[0:1], v[2:3], 0, s[82:83]
	s_add_i32 m0, s19, 0x1a000
	s_add_i32 s39, s19, 0x8000
	s_add_i32 s46, s19, 0xa000
	v_lshl_or_b32 v163, s4, 6, v135
	global_load_lds_dwordx4 v[0:1], off
	v_lshl_add_u64 v[0:1], v[6:7], 0, s[82:83]
	s_mov_b32 m0, s39
	s_add_u32 s4, s8, 0x40080
	global_load_lds_dwordx4 v[0:1], off
	v_lshl_add_u64 v[0:1], v[4:5], 0, s[82:83]
	s_mov_b32 m0, s46
	s_addc_u32 s5, s9, 0
	global_load_lds_dwordx4 v[0:1], off
	s_add_i32 m0, s19, 0x1c000
	v_lshl_add_u64 v[0:1], s[4:5], 0, v[174:175]
	global_load_lds_dwordx4 v[0:1], off
	v_lshl_add_u64 v[0:1], s[4:5], 0, v[132:133]
	s_add_i32 m0, s19, 0x1e000
	s_cmpk_lt_u32 s12, 0x100
	global_load_lds_dwordx4 v[0:1], off
	s_cselect_b64 s[28:29], -1, 0
	s_abs_i32 s55, s69
	v_cvt_f32_u32_e32 v0, s55
	v_lshlrev_b32_e32 v9, 2, v135
	v_lshl_or_b32 v8, v135, 6, v158
	v_and_b32_e32 v9, 32, v9
	v_rcp_iflag_f32_e32 v0, v0
	v_bitop3_b32 v8, v8, s2, v9 bitop3:0xde
	s_sub_i32 s2, 0, s55
	s_waitcnt vmcnt(6)
	v_mul_f32_e32 v0, 0x4f7ffffe, v0
	v_cvt_u32_f32_e32 v0, v0
	s_mov_b32 s72, s44
	v_lshl_or_b32 v164, s62, 12, v159
	s_ashr_i32 s47, s69, 31
	v_readfirstlane_b32 s3, v0
	s_mul_i32 s2, s2, s3
	s_mul_hi_u32 s2, s3, s2
	s_mov_b32 s99, 0
	s_add_i32 s59, s3, s2
	v_add_u32_e32 v165, 0, v8
	v_writelane_b32 v246, s89, 27
	s_barrier
	s_mov_b32 s30, 0
	v_writelane_b32 v246, s30, 42
	s_branch .LBB0_235

.LBB0_241:
	s_ashr_i32 s35, s34, 31
	s_lshl_b64 s[12:13], s[34:35], 19
	s_add_u32 s36, s40, s12
	s_addc_u32 s37, s41, s13
	s_and_b64 s[12:13], s[4:5], exec
	s_cselect_b32 s7, s37, s11
	s_cselect_b32 s35, s36, s10
	s_ashr_i32 s31, s30, 31
	s_lshl_b64 s[12:13], s[30:31], 19
	s_add_u32 s50, s42, s12
	s_addc_u32 s51, s43, s13
	s_and_b64 s[12:13], s[4:5], exec
	s_cselect_b32 s31, s51, s9
	s_cselect_b32 s89, s50, s8
	s_add_u32 vcc_lo, s8, 0x100
	s_addc_u32 vcc_hi, s9, 0
	s_add_u32 s8, s10, 0x40080
	v_mov_b32_e32 v0, 0
	s_addc_u32 s9, s11, 0
	s_mov_b32 s12, -2
	v_mov_b32_e32 v1, v0
	v_mov_b32_e32 v2, v0
	v_mov_b32_e32 v3, v0
	v_mov_b32_e32 v4, v0
	v_mov_b32_e32 v5, v0
	v_mov_b32_e32 v6, v0
	v_mov_b32_e32 v7, v0
	v_mov_b32_e32 v16, v0
	v_mov_b32_e32 v17, v0
	v_mov_b32_e32 v18, v0
	v_mov_b32_e32 v19, v0
	v_mov_b32_e32 v20, v0
	v_mov_b32_e32 v21, v0
	v_mov_b32_e32 v22, v0
	v_mov_b32_e32 v23, v0
	v_mov_b32_e32 v32, v0
	v_mov_b32_e32 v33, v0
	v_mov_b32_e32 v34, v0
	v_mov_b32_e32 v35, v0
	v_mov_b32_e32 v36, v0
	v_mov_b32_e32 v37, v0
	v_mov_b32_e32 v38, v0
	v_mov_b32_e32 v39, v0
	v_mov_b32_e32 v48, v0
	v_mov_b32_e32 v49, v0
	v_mov_b32_e32 v50, v0
	v_mov_b32_e32 v51, v0
	v_mov_b32_e32 v52, v0
	v_mov_b32_e32 v53, v0
	v_mov_b32_e32 v54, v0
	v_mov_b32_e32 v55, v0
	v_mov_b32_e32 v8, v0
	v_mov_b32_e32 v9, v0
	v_mov_b32_e32 v10, v0
	v_mov_b32_e32 v11, v0
	v_mov_b32_e32 v12, v0
	v_mov_b32_e32 v13, v0
	v_mov_b32_e32 v14, v0
	v_mov_b32_e32 v15, v0
	v_mov_b32_e32 v24, v0
	v_mov_b32_e32 v25, v0
	v_mov_b32_e32 v26, v0
	v_mov_b32_e32 v27, v0
	v_mov_b32_e32 v28, v0
	v_mov_b32_e32 v29, v0
	v_mov_b32_e32 v30, v0
	v_mov_b32_e32 v31, v0
	v_mov_b32_e32 v40, v0
	v_mov_b32_e32 v41, v0
	v_mov_b32_e32 v42, v0
	v_mov_b32_e32 v43, v0
	v_mov_b32_e32 v44, v0
	v_mov_b32_e32 v45, v0
	v_mov_b32_e32 v46, v0
	v_mov_b32_e32 v47, v0
	v_mov_b32_e32 v56, v0
	v_mov_b32_e32 v57, v0
	v_mov_b32_e32 v58, v0
	v_mov_b32_e32 v59, v0
	v_mov_b32_e32 v60, v0
	v_mov_b32_e32 v61, v0
	v_mov_b32_e32 v62, v0
	v_mov_b32_e32 v63, v0
	v_mov_b32_e32 v64, v0
	v_mov_b32_e32 v65, v0
	v_mov_b32_e32 v66, v0
	v_mov_b32_e32 v67, v0
	v_mov_b32_e32 v68, v0
	v_mov_b32_e32 v69, v0
	v_mov_b32_e32 v70, v0
	v_mov_b32_e32 v71, v0
	v_mov_b32_e32 v80, v0
	v_mov_b32_e32 v81, v0
	v_mov_b32_e32 v82, v0
	v_mov_b32_e32 v83, v0
	v_mov_b32_e32 v84, v0
	v_mov_b32_e32 v85, v0
	v_mov_b32_e32 v86, v0
	v_mov_b32_e32 v87, v0
	v_mov_b32_e32 v96, v0
	v_mov_b32_e32 v97, v0
	v_mov_b32_e32 v98, v0
	v_mov_b32_e32 v99, v0
	v_mov_b32_e32 v100, v0
	v_mov_b32_e32 v101, v0
	v_mov_b32_e32 v102, v0
	v_mov_b32_e32 v103, v0
	v_mov_b32_e32 v112, v0
	v_mov_b32_e32 v113, v0
	v_mov_b32_e32 v114, v0
	v_mov_b32_e32 v115, v0
	v_mov_b32_e32 v116, v0
	v_mov_b32_e32 v117, v0
	v_mov_b32_e32 v118, v0
	v_mov_b32_e32 v119, v0
	v_mov_b32_e32 v72, v0
	v_mov_b32_e32 v73, v0
	v_mov_b32_e32 v74, v0
	v_mov_b32_e32 v75, v0
	v_mov_b32_e32 v76, v0
	v_mov_b32_e32 v77, v0
	v_mov_b32_e32 v78, v0
	v_mov_b32_e32 v79, v0
	v_mov_b32_e32 v88, v0
	v_mov_b32_e32 v89, v0
	v_mov_b32_e32 v90, v0
	v_mov_b32_e32 v91, v0
	v_mov_b32_e32 v92, v0
	v_mov_b32_e32 v93, v0
	v_mov_b32_e32 v94, v0
	v_mov_b32_e32 v95, v0
	v_mov_b32_e32 v104, v0
	v_mov_b32_e32 v105, v0
	v_mov_b32_e32 v106, v0
	v_mov_b32_e32 v107, v0
	v_mov_b32_e32 v108, v0
	v_mov_b32_e32 v109, v0
	v_mov_b32_e32 v110, v0
	v_mov_b32_e32 v111, v0
	v_mov_b32_e32 v120, v0
	v_mov_b32_e32 v121, v0
	v_mov_b32_e32 v122, v0
	v_mov_b32_e32 v123, v0
	v_mov_b32_e32 v124, v0
	v_mov_b32_e32 v125, v0
	v_mov_b32_e32 v126, v0
	v_mov_b32_e32 v127, v0
	v_readlane_b32 s2, v246, 42
	s_cmp_eq_u32 s2, 0
	s_cbranch_scc1 .LBB0_242
	s_add_u32 s2, s8, 0xfffc0080
	s_addc_u32 s3, s9, -1
	s_add_i32 s13, 0, 0x10000
	s_cmp_eq_u32 s12, 12
	s_cselect_b32 s53, s7, s3
	s_cselect_b32 s52, s35, s2
	v_add_u32_e32 v156, s13, v164
	s_cselect_b32 s11, s31, vcc_hi
	s_cselect_b32 s10, s89, vcc_lo
	s_add_i32 s77, 0, 0x14000
	ds_read_b128 v[144:147], v156
	ds_read_b128 v[148:151], v156 offset:1024
	ds_read_b128 v[152:155], v156 offset:2048
	ds_read_b128 v[166:169], v156 offset:3072
	v_add_u32_e32 v156, s77, v164
	ds_read_b128 v[184:187], v156
	ds_read_b128 v[188:191], v156 offset:1024
	ds_read_b128 v[192:195], v156 offset:2048
	ds_read_b128 v[196:199], v156 offset:3072
	v_lshl_add_u64 v[156:157], s[8:9], 0, v[142:143]
	s_add_i32 m0, s19, 0xc000
	ds_read_b128 v[200:203], v165
	ds_read_b128 v[210:213], v165 offset:1024
	ds_read_b128 v[214:217], v165 offset:2048
	ds_read_b128 v[218:221], v165 offset:3072
	ds_read_b128 v[222:225], v165 offset:4096
	ds_read_b128 v[226:229], v165 offset:5120
	ds_read_b128 v[230:233], v165 offset:6144
	ds_read_b128 v[234:237], v165 offset:7168
	global_load_lds_dwordx4 v[156:157], off
	v_lshl_add_u64 v[156:157], s[8:9], 0, v[140:141]
	s_add_i32 m0, s19, 0xe000
	s_nop 0
	global_load_lds_dwordx4 v[156:157], off
	s_waitcnt vmcnt(24)
	s_waitcnt lgkmcnt(0)
	s_barrier
	s_setprio 1
	s_waitcnt lgkmcnt(0)
	v_mfma_f32_16x16x32_bf16 v[124:127], v[144:147], v[200:203], v[124:127]
	v_mfma_f32_16x16x32_bf16 v[124:127], v[148:151], v[210:213], v[124:127]
	v_mfma_f32_16x16x32_bf16 v[120:123], v[152:155], v[200:203], v[120:123]
	v_mfma_f32_16x16x32_bf16 v[120:123], v[166:169], v[210:213], v[120:123]
	v_mfma_f32_16x16x32_bf16 v[108:111], v[144:147], v[214:217], v[108:111]
	v_mfma_f32_16x16x32_bf16 v[108:111], v[148:151], v[218:221], v[108:111]
	v_mfma_f32_16x16x32_bf16 v[104:107], v[152:155], v[214:217], v[104:107]
	v_mfma_f32_16x16x32_bf16 v[104:107], v[166:169], v[218:221], v[104:107]
	v_mfma_f32_16x16x32_bf16 v[92:95], v[144:147], v[222:225], v[92:95]
	v_mfma_f32_16x16x32_bf16 v[92:95], v[148:151], v[226:229], v[92:95]
	v_mfma_f32_16x16x32_bf16 v[88:91], v[152:155], v[222:225], v[88:91]
	v_mfma_f32_16x16x32_bf16 v[88:91], v[166:169], v[226:229], v[88:91]
	v_mfma_f32_16x16x32_bf16 v[76:79], v[144:147], v[230:233], v[76:79]
	v_mfma_f32_16x16x32_bf16 v[76:79], v[148:151], v[234:237], v[76:79]
	v_mfma_f32_16x16x32_bf16 v[72:75], v[152:155], v[230:233], v[72:75]
	v_mfma_f32_16x16x32_bf16 v[72:75], v[166:169], v[234:237], v[72:75]
	s_setprio 0
	s_setprio 1
	v_mfma_f32_16x16x32_bf16 v[116:119], v[184:187], v[200:203], v[116:119]
	v_mfma_f32_16x16x32_bf16 v[116:119], v[188:191], v[210:213], v[116:119]
	v_mfma_f32_16x16x32_bf16 v[112:115], v[192:195], v[200:203], v[112:115]
	v_mfma_f32_16x16x32_bf16 v[112:115], v[196:199], v[210:213], v[112:115]
	v_mfma_f32_16x16x32_bf16 v[100:103], v[184:187], v[214:217], v[100:103]
	v_mfma_f32_16x16x32_bf16 v[100:103], v[188:191], v[218:221], v[100:103]
	v_mfma_f32_16x16x32_bf16 v[96:99], v[192:195], v[214:217], v[96:99]
	v_mfma_f32_16x16x32_bf16 v[96:99], v[196:199], v[218:221], v[96:99]
	v_mfma_f32_16x16x32_bf16 v[84:87], v[184:187], v[222:225], v[84:87]
	v_mfma_f32_16x16x32_bf16 v[84:87], v[188:191], v[226:229], v[84:87]
	v_mfma_f32_16x16x32_bf16 v[80:83], v[192:195], v[222:225], v[80:83]
	v_mfma_f32_16x16x32_bf16 v[80:83], v[196:199], v[226:229], v[80:83]
	v_mfma_f32_16x16x32_bf16 v[68:71], v[184:187], v[230:233], v[68:71]
	v_mfma_f32_16x16x32_bf16 v[68:71], v[188:191], v[234:237], v[68:71]
	v_mfma_f32_16x16x32_bf16 v[64:67], v[192:195], v[230:233], v[64:67]
	v_mfma_f32_16x16x32_bf16 v[64:67], v[196:199], v[234:237], v[64:67]
	s_setprio 0
	s_barrier
	s_add_i32 s2, s13, s56
	v_lshl_add_u64 v[156:157], s[10:11], 0, v[174:175]
	s_mov_b32 m0, s2
	ds_read_b128 v[200:203], v165 offset:16384
	ds_read_b128 v[210:213], v165 offset:17408
	ds_read_b128 v[214:217], v165 offset:18432
	ds_read_b128 v[218:221], v165 offset:19456
	ds_read_b128 v[222:225], v165 offset:20480
	ds_read_b128 v[226:229], v165 offset:21504
	ds_read_b128 v[230:233], v165 offset:22528
	ds_read_b128 v[234:237], v165 offset:23552
	global_load_lds_dwordx4 v[156:157], off
	s_add_i32 m0, s2, 0x2000
	s_add_u32 s2, s10, 0x40000
	v_lshl_add_u64 v[170:171], s[10:11], 0, v[132:133]
	s_addc_u32 s3, s11, 0
	s_add_i32 s13, s77, s56
	global_load_lds_dwordx4 v[170:171], off
	v_lshl_add_u64 v[238:239], s[2:3], 0, v[174:175]
	s_mov_b32 m0, s13
	v_lshl_add_u64 v[240:241], s[52:53], 0, v[130:131]
	global_load_lds_dwordx4 v[238:239], off
	v_lshl_add_u64 v[238:239], s[2:3], 0, v[132:133]
	s_add_i32 m0, s13, 0x2000
	s_nop 0
	global_load_lds_dwordx4 v[238:239], off
	v_lshl_add_u64 v[238:239], s[52:53], 0, v[128:129]
	s_mov_b32 m0, s19
	s_nop 0
	global_load_lds_dwordx4 v[238:239], off
	s_mov_b32 m0, s57
	s_nop 0
	global_load_lds_dwordx4 v[240:241], off
	s_waitcnt vmcnt(24)
	s_waitcnt lgkmcnt(0)
	s_barrier
	s_setprio 1
	s_waitcnt lgkmcnt(0)
	v_mfma_f32_16x16x32_bf16 v[60:63], v[144:147], v[200:203], v[60:63]
	v_mfma_f32_16x16x32_bf16 v[60:63], v[148:151], v[210:213], v[60:63]
	v_mfma_f32_16x16x32_bf16 v[56:59], v[152:155], v[200:203], v[56:59]
	v_mfma_f32_16x16x32_bf16 v[56:59], v[166:169], v[210:213], v[56:59]
	v_mfma_f32_16x16x32_bf16 v[44:47], v[144:147], v[214:217], v[44:47]
	v_mfma_f32_16x16x32_bf16 v[44:47], v[148:151], v[218:221], v[44:47]
	v_mfma_f32_16x16x32_bf16 v[40:43], v[152:155], v[214:217], v[40:43]
	v_mfma_f32_16x16x32_bf16 v[40:43], v[166:169], v[218:221], v[40:43]
	v_mfma_f32_16x16x32_bf16 v[28:31], v[144:147], v[222:225], v[28:31]
	v_mfma_f32_16x16x32_bf16 v[28:31], v[148:151], v[226:229], v[28:31]
	v_mfma_f32_16x16x32_bf16 v[24:27], v[152:155], v[222:225], v[24:27]
	v_mfma_f32_16x16x32_bf16 v[24:27], v[166:169], v[226:229], v[24:27]
	v_mfma_f32_16x16x32_bf16 v[12:15], v[144:147], v[230:233], v[12:15]
	v_mfma_f32_16x16x32_bf16 v[12:15], v[148:151], v[234:237], v[12:15]
	v_mfma_f32_16x16x32_bf16 v[8:11], v[152:155], v[230:233], v[8:11]
	v_mfma_f32_16x16x32_bf16 v[8:11], v[166:169], v[234:237], v[8:11]
	s_setprio 0
	s_setprio 1
	v_mfma_f32_16x16x32_bf16 v[52:55], v[184:187], v[200:203], v[52:55]
	v_mfma_f32_16x16x32_bf16 v[52:55], v[188:191], v[210:213], v[52:55]
	v_mfma_f32_16x16x32_bf16 v[48:51], v[192:195], v[200:203], v[48:51]
	v_mfma_f32_16x16x32_bf16 v[48:51], v[196:199], v[210:213], v[48:51]
	v_mfma_f32_16x16x32_bf16 v[36:39], v[184:187], v[214:217], v[36:39]
	v_mfma_f32_16x16x32_bf16 v[36:39], v[188:191], v[218:221], v[36:39]
	v_mfma_f32_16x16x32_bf16 v[32:35], v[192:195], v[214:217], v[32:35]
	v_mfma_f32_16x16x32_bf16 v[32:35], v[196:199], v[218:221], v[32:35]
	v_mfma_f32_16x16x32_bf16 v[20:23], v[184:187], v[222:225], v[20:23]
	v_mfma_f32_16x16x32_bf16 v[20:23], v[188:191], v[226:229], v[20:23]
	v_mfma_f32_16x16x32_bf16 v[16:19], v[192:195], v[222:225], v[16:19]
	v_mfma_f32_16x16x32_bf16 v[16:19], v[196:199], v[226:229], v[16:19]
	v_mfma_f32_16x16x32_bf16 v[4:7], v[184:187], v[230:233], v[4:7]
	v_mfma_f32_16x16x32_bf16 v[4:7], v[188:191], v[234:237], v[4:7]
	v_mfma_f32_16x16x32_bf16 v[0:3], v[192:195], v[230:233], v[0:3]
	v_mfma_f32_16x16x32_bf16 v[0:3], v[196:199], v[234:237], v[0:3]
	s_setprio 0
	s_barrier
	s_add_i32 s13, 0, 0x18000
	s_add_i32 s77, 0, 0x1c000
	v_add_u32_e32 v166, s13, v164
	v_add_u32_e32 v183, s77, v164
	ds_read_b128 v[144:147], v166
	ds_read_b128 v[148:151], v166 offset:1024
	ds_read_b128 v[152:155], v166 offset:2048
	ds_read_b128 v[166:169], v166 offset:3072
	ds_read_b128 v[184:187], v183
	ds_read_b128 v[188:191], v183 offset:1024
	ds_read_b128 v[192:195], v183 offset:2048
	ds_read_b128 v[196:199], v183 offset:3072
	s_add_u32 s2, s52, 0x40000
	s_addc_u32 s3, s53, 0
	s_mov_b32 m0, s60
	v_lshl_add_u64 v[242:243], s[2:3], 0, v[128:129]
	ds_read_b128 v[200:203], v165 offset:32768
	ds_read_b128 v[210:213], v165 offset:33792
	ds_read_b128 v[214:217], v165 offset:34816
	ds_read_b128 v[218:221], v165 offset:35840
	ds_read_b128 v[222:225], v165 offset:36864
	ds_read_b128 v[226:229], v165 offset:37888
	ds_read_b128 v[230:233], v165 offset:38912
	ds_read_b128 v[234:237], v165 offset:39936
	global_load_lds_dwordx4 v[242:243], off
	v_lshl_add_u64 v[242:243], s[2:3], 0, v[130:131]
	s_mov_b32 m0, s61
	s_nop 0
	global_load_lds_dwordx4 v[242:243], off
	s_waitcnt vmcnt(8)
	s_waitcnt lgkmcnt(0)
	s_barrier
	s_setprio 1
	s_waitcnt lgkmcnt(0)
	v_mfma_f32_16x16x32_bf16 v[124:127], v[144:147], v[200:203], v[124:127]
	v_mfma_f32_16x16x32_bf16 v[124:127], v[148:151], v[210:213], v[124:127]
	v_mfma_f32_16x16x32_bf16 v[120:123], v[152:155], v[200:203], v[120:123]
	v_mfma_f32_16x16x32_bf16 v[120:123], v[166:169], v[210:213], v[120:123]
	v_mfma_f32_16x16x32_bf16 v[108:111], v[144:147], v[214:217], v[108:111]
	v_mfma_f32_16x16x32_bf16 v[108:111], v[148:151], v[218:221], v[108:111]
	v_mfma_f32_16x16x32_bf16 v[104:107], v[152:155], v[214:217], v[104:107]
	v_mfma_f32_16x16x32_bf16 v[104:107], v[166:169], v[218:221], v[104:107]
	v_mfma_f32_16x16x32_bf16 v[92:95], v[144:147], v[222:225], v[92:95]
	v_mfma_f32_16x16x32_bf16 v[92:95], v[148:151], v[226:229], v[92:95]
	v_mfma_f32_16x16x32_bf16 v[88:91], v[152:155], v[222:225], v[88:91]
	v_mfma_f32_16x16x32_bf16 v[88:91], v[166:169], v[226:229], v[88:91]
	v_mfma_f32_16x16x32_bf16 v[76:79], v[144:147], v[230:233], v[76:79]
	v_mfma_f32_16x16x32_bf16 v[76:79], v[148:151], v[234:237], v[76:79]
	v_mfma_f32_16x16x32_bf16 v[72:75], v[152:155], v[230:233], v[72:75]
	v_mfma_f32_16x16x32_bf16 v[72:75], v[166:169], v[234:237], v[72:75]
	s_setprio 0
	s_setprio 1
	v_mfma_f32_16x16x32_bf16 v[116:119], v[184:187], v[200:203], v[116:119]
	v_mfma_f32_16x16x32_bf16 v[116:119], v[188:191], v[210:213], v[116:119]
	v_mfma_f32_16x16x32_bf16 v[112:115], v[192:195], v[200:203], v[112:115]
	v_mfma_f32_16x16x32_bf16 v[112:115], v[196:199], v[210:213], v[112:115]
	v_mfma_f32_16x16x32_bf16 v[100:103], v[184:187], v[214:217], v[100:103]
	v_mfma_f32_16x16x32_bf16 v[100:103], v[188:191], v[218:221], v[100:103]
	v_mfma_f32_16x16x32_bf16 v[96:99], v[192:195], v[214:217], v[96:99]
	v_mfma_f32_16x16x32_bf16 v[96:99], v[196:199], v[218:221], v[96:99]
	v_mfma_f32_16x16x32_bf16 v[84:87], v[184:187], v[222:225], v[84:87]
	v_mfma_f32_16x16x32_bf16 v[84:87], v[188:191], v[226:229], v[84:87]
	v_mfma_f32_16x16x32_bf16 v[80:83], v[192:195], v[222:225], v[80:83]
	v_mfma_f32_16x16x32_bf16 v[80:83], v[196:199], v[226:229], v[80:83]
	v_mfma_f32_16x16x32_bf16 v[68:71], v[184:187], v[230:233], v[68:71]
	v_mfma_f32_16x16x32_bf16 v[68:71], v[188:191], v[234:237], v[68:71]
	v_mfma_f32_16x16x32_bf16 v[64:67], v[192:195], v[230:233], v[64:67]
	v_mfma_f32_16x16x32_bf16 v[64:67], v[196:199], v[234:237], v[64:67]
	s_setprio 0
	s_barrier
	s_add_i32 s2, s13, s56
	v_lshl_add_u64 v[156:157], v[156:157], 0, s[82:83]
	s_mov_b32 m0, s2
	ds_read_b128 v[200:203], v165 offset:49152
	ds_read_b128 v[210:213], v165 offset:50176
	ds_read_b128 v[214:217], v165 offset:51200
	ds_read_b128 v[218:221], v165 offset:52224
	ds_read_b128 v[222:225], v165 offset:53248
	ds_read_b128 v[226:229], v165 offset:54272
	ds_read_b128 v[230:233], v165 offset:55296
	ds_read_b128 v[234:237], v165 offset:56320
	global_load_lds_dwordx4 v[156:157], off
	s_add_i32 m0, s2, 0x2000
	s_add_u32 s2, s10, 0x40080
	v_lshl_add_u64 v[156:157], v[170:171], 0, s[82:83]
	s_addc_u32 s3, s11, 0
	s_add_i32 s10, s77, s56
	global_load_lds_dwordx4 v[156:157], off
	v_lshl_add_u64 v[156:157], s[2:3], 0, v[174:175]
	s_mov_b32 m0, s10
	s_nop 0
	global_load_lds_dwordx4 v[156:157], off
	v_lshl_add_u64 v[156:157], s[2:3], 0, v[132:133]
	s_add_i32 m0, s10, 0x2000
	s_nop 0
	global_load_lds_dwordx4 v[156:157], off
	v_lshl_add_u64 v[156:157], v[238:239], 0, s[82:83]
	s_mov_b32 m0, s39
	s_nop 0
	global_load_lds_dwordx4 v[156:157], off
	v_lshl_add_u64 v[156:157], v[240:241], 0, s[82:83]
	s_mov_b32 m0, s46
	s_nop 0
	global_load_lds_dwordx4 v[156:157], off
	s_waitcnt vmcnt(8)
	s_waitcnt lgkmcnt(0)
	s_barrier
	s_setprio 1
	s_waitcnt lgkmcnt(0)
	v_mfma_f32_16x16x32_bf16 v[60:63], v[144:147], v[200:203], v[60:63]
	v_mfma_f32_16x16x32_bf16 v[60:63], v[148:151], v[210:213], v[60:63]
	v_mfma_f32_16x16x32_bf16 v[56:59], v[152:155], v[200:203], v[56:59]
	v_mfma_f32_16x16x32_bf16 v[56:59], v[166:169], v[210:213], v[56:59]
	v_mfma_f32_16x16x32_bf16 v[44:47], v[144:147], v[214:217], v[44:47]
	v_mfma_f32_16x16x32_bf16 v[44:47], v[148:151], v[218:221], v[44:47]
	v_mfma_f32_16x16x32_bf16 v[40:43], v[152:155], v[214:217], v[40:43]
	v_mfma_f32_16x16x32_bf16 v[40:43], v[166:169], v[218:221], v[40:43]
	v_mfma_f32_16x16x32_bf16 v[28:31], v[144:147], v[222:225], v[28:31]
	v_mfma_f32_16x16x32_bf16 v[28:31], v[148:151], v[226:229], v[28:31]
	v_mfma_f32_16x16x32_bf16 v[24:27], v[152:155], v[222:225], v[24:27]
	v_mfma_f32_16x16x32_bf16 v[24:27], v[166:169], v[226:229], v[24:27]
	v_mfma_f32_16x16x32_bf16 v[12:15], v[144:147], v[230:233], v[12:15]
	v_mfma_f32_16x16x32_bf16 v[12:15], v[148:151], v[234:237], v[12:15]
	v_mfma_f32_16x16x32_bf16 v[8:11], v[152:155], v[230:233], v[8:11]
	v_mfma_f32_16x16x32_bf16 v[8:11], v[166:169], v[234:237], v[8:11]
	s_setprio 0
	s_setprio 1
	v_mfma_f32_16x16x32_bf16 v[52:55], v[184:187], v[200:203], v[52:55]
	v_mfma_f32_16x16x32_bf16 v[52:55], v[188:191], v[210:213], v[52:55]
	v_mfma_f32_16x16x32_bf16 v[48:51], v[192:195], v[200:203], v[48:51]
	v_mfma_f32_16x16x32_bf16 v[48:51], v[196:199], v[210:213], v[48:51]
	v_mfma_f32_16x16x32_bf16 v[36:39], v[184:187], v[214:217], v[36:39]
	v_mfma_f32_16x16x32_bf16 v[36:39], v[188:191], v[218:221], v[36:39]
	v_mfma_f32_16x16x32_bf16 v[32:35], v[192:195], v[214:217], v[32:35]
	v_mfma_f32_16x16x32_bf16 v[32:35], v[196:199], v[218:221], v[32:35]
	v_mfma_f32_16x16x32_bf16 v[20:23], v[184:187], v[222:225], v[20:23]
	v_mfma_f32_16x16x32_bf16 v[20:23], v[188:191], v[226:229], v[20:23]
	v_mfma_f32_16x16x32_bf16 v[16:19], v[192:195], v[222:225], v[16:19]
	v_mfma_f32_16x16x32_bf16 v[16:19], v[196:199], v[226:229], v[16:19]
	v_mfma_f32_16x16x32_bf16 v[4:7], v[184:187], v[230:233], v[4:7]
	v_mfma_f32_16x16x32_bf16 v[4:7], v[188:191], v[234:237], v[4:7]
	v_mfma_f32_16x16x32_bf16 v[0:3], v[192:195], v[230:233], v[0:3]
	v_mfma_f32_16x16x32_bf16 v[0:3], v[196:199], v[234:237], v[0:3]
	s_setprio 0
	s_barrier
	s_add_i32 s12, s12, 2
	s_add_u32 vcc_lo, vcc_lo, 0x100
	s_addc_u32 vcc_hi, vcc_hi, 0
	s_add_u32 s8, s8, 0x100
	s_addc_u32 s9, s9, 0
	s_cmp_gt_u32 s12, 13
	s_cbranch_scc1 .Lexit_242

.Lexit_242:
	s_and_b64 vcc, exec, s[28:29]
	s_cbranch_vccz .LBB0_245
	s_barrier
.LBB0_245:
	s_mov_b32 s2, 1
	v_writelane_b32 v246, s2, 42
	s_cmp_lg_u32 s95, 2
	s_cbranch_scc1 .Lepi_generic
	s_or_b64 s[2:3], s[24:25], s[22:23]
	s_and_b64 vcc, exec, s[2:3]
	s_cbranch_vccnz .Lepi_generic
	s_and_b64 vcc, exec, s[26:27]
	s_cbranch_vccz .Lepi_generic
	v_lshl_add_u32 v156, s6, 8, v163
	s_lshl_b32 s2, s18, 8
	s_or_b32 s2, s2, s38
	v_or_b32_e32 v157, s2, v137
	v_mul_lo_u32 v156, v156, s33
	v_add_lshl_u32 v156, v156, v157, 1
	v_max_f32_e32 v124, 0, v124
	v_max_f32_e32 v125, 0, v125
	v_max_f32_e32 v126, 0, v126
	v_max_f32_e32 v127, 0, v127
	v_max_f32_e32 v120, 0, v120
	v_max_f32_e32 v121, 0, v121
	v_max_f32_e32 v122, 0, v122
	v_max_f32_e32 v123, 0, v123
	v_mul_f32_e32 v124, v124, v124
	v_mul_f32_e32 v125, v125, v125
	v_mul_f32_e32 v126, v126, v126
	v_mul_f32_e32 v127, v127, v127
	v_mul_f32_e32 v120, v120, v120
	v_mul_f32_e32 v121, v121, v121
	v_mul_f32_e32 v122, v122, v122
	v_mul_f32_e32 v123, v123, v123
	v_cvt_pk_bf16_f32 v144, v124, v125
	v_cvt_pk_bf16_f32 v145, v126, v127
	v_cvt_pk_bf16_f32 v146, v120, v121
	v_cvt_pk_bf16_f32 v147, v122, v123
	buffer_store_dwordx4 v[144:147], v156, s[72:75], 0 offen
	v_max_f32_e32 v116, 0, v116
	v_max_f32_e32 v117, 0, v117
	v_max_f32_e32 v118, 0, v118
	v_max_f32_e32 v119, 0, v119
	v_max_f32_e32 v112, 0, v112
	v_max_f32_e32 v113, 0, v113
	v_max_f32_e32 v114, 0, v114
	v_max_f32_e32 v115, 0, v115
	v_mul_f32_e32 v116, v116, v116
	v_mul_f32_e32 v117, v117, v117
	v_mul_f32_e32 v118, v118, v118
	v_mul_f32_e32 v119, v119, v119
	v_mul_f32_e32 v112, v112, v112
	v_mul_f32_e32 v113, v113, v113
	v_mul_f32_e32 v114, v114, v114
	v_mul_f32_e32 v115, v115, v115
	v_cvt_pk_bf16_f32 v152, v116, v117
	v_cvt_pk_bf16_f32 v153, v118, v119
	v_cvt_pk_bf16_f32 v154, v112, v113
	v_cvt_pk_bf16_f32 v155, v114, v115
	buffer_store_dwordx4 v[152:155], v156, s[72:75], 0 offen offset:256
	s_mul_i32 s2, s33, 0x20
	v_max_f32_e32 v108, 0, v108
	v_max_f32_e32 v109, 0, v109
	v_max_f32_e32 v110, 0, v110
	v_max_f32_e32 v111, 0, v111
	v_max_f32_e32 v104, 0, v104
	v_max_f32_e32 v105, 0, v105
	v_max_f32_e32 v106, 0, v106
	v_max_f32_e32 v107, 0, v107
	v_mul_f32_e32 v108, v108, v108
	v_mul_f32_e32 v109, v109, v109
	v_mul_f32_e32 v110, v110, v110
	v_mul_f32_e32 v111, v111, v111
	v_mul_f32_e32 v104, v104, v104
	v_mul_f32_e32 v105, v105, v105
	v_mul_f32_e32 v106, v106, v106
	v_mul_f32_e32 v107, v107, v107
	v_cvt_pk_bf16_f32 v144, v108, v109
	v_cvt_pk_bf16_f32 v145, v110, v111
	v_cvt_pk_bf16_f32 v146, v104, v105
	v_cvt_pk_bf16_f32 v147, v106, v107
	buffer_store_dwordx4 v[144:147], v156, s[72:75], s2 offen
	v_max_f32_e32 v100, 0, v100
	v_max_f32_e32 v101, 0, v101
	v_max_f32_e32 v102, 0, v102
	v_max_f32_e32 v103, 0, v103
	v_max_f32_e32 v96, 0, v96
	v_max_f32_e32 v97, 0, v97
	v_max_f32_e32 v98, 0, v98
	v_max_f32_e32 v99, 0, v99
	v_mul_f32_e32 v100, v100, v100
	v_mul_f32_e32 v101, v101, v101
	v_mul_f32_e32 v102, v102, v102
	v_mul_f32_e32 v103, v103, v103
	v_mul_f32_e32 v96, v96, v96
	v_mul_f32_e32 v97, v97, v97
	v_mul_f32_e32 v98, v98, v98
	v_mul_f32_e32 v99, v99, v99
	v_cvt_pk_bf16_f32 v152, v100, v101
	v_cvt_pk_bf16_f32 v153, v102, v103
	v_cvt_pk_bf16_f32 v154, v96, v97
	v_cvt_pk_bf16_f32 v155, v98, v99
	buffer_store_dwordx4 v[152:155], v156, s[72:75], s2 offen offset:256
	s_mul_i32 s2, s33, 0x40
	v_max_f32_e32 v92, 0, v92
	v_max_f32_e32 v93, 0, v93
	v_max_f32_e32 v94, 0, v94
	v_max_f32_e32 v95, 0, v95
	v_max_f32_e32 v88, 0, v88
	v_max_f32_e32 v89, 0, v89
	v_max_f32_e32 v90, 0, v90
	v_max_f32_e32 v91, 0, v91
	v_mul_f32_e32 v92, v92, v92
	v_mul_f32_e32 v93, v93, v93
	v_mul_f32_e32 v94, v94, v94
	v_mul_f32_e32 v95, v95, v95
	v_mul_f32_e32 v88, v88, v88
	v_mul_f32_e32 v89, v89, v89
	v_mul_f32_e32 v90, v90, v90
	v_mul_f32_e32 v91, v91, v91
	v_cvt_pk_bf16_f32 v144, v92, v93
	v_cvt_pk_bf16_f32 v145, v94, v95
	v_cvt_pk_bf16_f32 v146, v88, v89
	v_cvt_pk_bf16_f32 v147, v90, v91
	buffer_store_dwordx4 v[144:147], v156, s[72:75], s2 offen
	v_max_f32_e32 v84, 0, v84
	v_max_f32_e32 v85, 0, v85
	v_max_f32_e32 v86, 0, v86
	v_max_f32_e32 v87, 0, v87
	v_max_f32_e32 v80, 0, v80
	v_max_f32_e32 v81, 0, v81
	v_max_f32_e32 v82, 0, v82
	v_max_f32_e32 v83, 0, v83
	v_mul_f32_e32 v84, v84, v84
	v_mul_f32_e32 v85, v85, v85
	v_mul_f32_e32 v86, v86, v86
	v_mul_f32_e32 v87, v87, v87
	v_mul_f32_e32 v80, v80, v80
	v_mul_f32_e32 v81, v81, v81
	v_mul_f32_e32 v82, v82, v82
	v_mul_f32_e32 v83, v83, v83
	v_cvt_pk_bf16_f32 v152, v84, v85
	v_cvt_pk_bf16_f32 v153, v86, v87
	v_cvt_pk_bf16_f32 v154, v80, v81
	v_cvt_pk_bf16_f32 v155, v82, v83
	buffer_store_dwordx4 v[152:155], v156, s[72:75], s2 offen offset:256
	s_mul_i32 s2, s33, 0x60
	v_max_f32_e32 v76, 0, v76
	v_max_f32_e32 v77, 0, v77
	v_max_f32_e32 v78, 0, v78
	v_max_f32_e32 v79, 0, v79
	v_max_f32_e32 v72, 0, v72
	v_max_f32_e32 v73, 0, v73
	v_max_f32_e32 v74, 0, v74
	v_max_f32_e32 v75, 0, v75
	v_mul_f32_e32 v76, v76, v76
	v_mul_f32_e32 v77, v77, v77
	v_mul_f32_e32 v78, v78, v78
	v_mul_f32_e32 v79, v79, v79
	v_mul_f32_e32 v72, v72, v72
	v_mul_f32_e32 v73, v73, v73
	v_mul_f32_e32 v74, v74, v74
	v_mul_f32_e32 v75, v75, v75
	v_cvt_pk_bf16_f32 v144, v76, v77
	v_cvt_pk_bf16_f32 v145, v78, v79
	v_cvt_pk_bf16_f32 v146, v72, v73
	v_cvt_pk_bf16_f32 v147, v74, v75
	buffer_store_dwordx4 v[144:147], v156, s[72:75], s2 offen
	v_max_f32_e32 v68, 0, v68
	v_max_f32_e32 v69, 0, v69
	v_max_f32_e32 v70, 0, v70
	v_max_f32_e32 v71, 0, v71
	v_max_f32_e32 v64, 0, v64
	v_max_f32_e32 v65, 0, v65
	v_max_f32_e32 v66, 0, v66
	v_max_f32_e32 v67, 0, v67
	v_mul_f32_e32 v68, v68, v68
	v_mul_f32_e32 v69, v69, v69
	v_mul_f32_e32 v70, v70, v70
	v_mul_f32_e32 v71, v71, v71
	v_mul_f32_e32 v64, v64, v64
	v_mul_f32_e32 v65, v65, v65
	v_mul_f32_e32 v66, v66, v66
	v_mul_f32_e32 v67, v67, v67
	v_cvt_pk_bf16_f32 v152, v68, v69
	v_cvt_pk_bf16_f32 v153, v70, v71
	v_cvt_pk_bf16_f32 v154, v64, v65
	v_cvt_pk_bf16_f32 v155, v66, v67
	buffer_store_dwordx4 v[152:155], v156, s[72:75], s2 offen offset:256
	s_mul_i32 s2, s33, 0x100
	v_max_f32_e32 v60, 0, v60
	v_max_f32_e32 v61, 0, v61
	v_max_f32_e32 v62, 0, v62
	v_max_f32_e32 v63, 0, v63
	v_max_f32_e32 v56, 0, v56
	v_max_f32_e32 v57, 0, v57
	v_max_f32_e32 v58, 0, v58
	v_max_f32_e32 v59, 0, v59
	v_mul_f32_e32 v60, v60, v60
	v_mul_f32_e32 v61, v61, v61
	v_mul_f32_e32 v62, v62, v62
	v_mul_f32_e32 v63, v63, v63
	v_mul_f32_e32 v56, v56, v56
	v_mul_f32_e32 v57, v57, v57
	v_mul_f32_e32 v58, v58, v58
	v_mul_f32_e32 v59, v59, v59
	v_cvt_pk_bf16_f32 v144, v60, v61
	v_cvt_pk_bf16_f32 v145, v62, v63
	v_cvt_pk_bf16_f32 v146, v56, v57
	v_cvt_pk_bf16_f32 v147, v58, v59
	buffer_store_dwordx4 v[144:147], v156, s[72:75], s2 offen
	v_max_f32_e32 v52, 0, v52
	v_max_f32_e32 v53, 0, v53
	v_max_f32_e32 v54, 0, v54
	v_max_f32_e32 v55, 0, v55
	v_max_f32_e32 v48, 0, v48
	v_max_f32_e32 v49, 0, v49
	v_max_f32_e32 v50, 0, v50
	v_max_f32_e32 v51, 0, v51
	v_mul_f32_e32 v52, v52, v52
	v_mul_f32_e32 v53, v53, v53
	v_mul_f32_e32 v54, v54, v54
	v_mul_f32_e32 v55, v55, v55
	v_mul_f32_e32 v48, v48, v48
	v_mul_f32_e32 v49, v49, v49
	v_mul_f32_e32 v50, v50, v50
	v_mul_f32_e32 v51, v51, v51
	v_cvt_pk_bf16_f32 v152, v52, v53
	v_cvt_pk_bf16_f32 v153, v54, v55
	v_cvt_pk_bf16_f32 v154, v48, v49
	v_cvt_pk_bf16_f32 v155, v50, v51
	buffer_store_dwordx4 v[152:155], v156, s[72:75], s2 offen offset:256
	s_mul_i32 s2, s33, 0x120
	v_max_f32_e32 v44, 0, v44
	v_max_f32_e32 v45, 0, v45
	v_max_f32_e32 v46, 0, v46
	v_max_f32_e32 v47, 0, v47
	v_max_f32_e32 v40, 0, v40
	v_max_f32_e32 v41, 0, v41
	v_max_f32_e32 v42, 0, v42
	v_max_f32_e32 v43, 0, v43
	v_mul_f32_e32 v44, v44, v44
	v_mul_f32_e32 v45, v45, v45
	v_mul_f32_e32 v46, v46, v46
	v_mul_f32_e32 v47, v47, v47
	v_mul_f32_e32 v40, v40, v40
	v_mul_f32_e32 v41, v41, v41
	v_mul_f32_e32 v42, v42, v42
	v_mul_f32_e32 v43, v43, v43
	v_cvt_pk_bf16_f32 v144, v44, v45
	v_cvt_pk_bf16_f32 v145, v46, v47
	v_cvt_pk_bf16_f32 v146, v40, v41
	v_cvt_pk_bf16_f32 v147, v42, v43
	buffer_store_dwordx4 v[144:147], v156, s[72:75], s2 offen
	v_max_f32_e32 v36, 0, v36
	v_max_f32_e32 v37, 0, v37
	v_max_f32_e32 v38, 0, v38
	v_max_f32_e32 v39, 0, v39
	v_max_f32_e32 v32, 0, v32
	v_max_f32_e32 v33, 0, v33
	v_max_f32_e32 v34, 0, v34
	v_max_f32_e32 v35, 0, v35
	v_mul_f32_e32 v36, v36, v36
	v_mul_f32_e32 v37, v37, v37
	v_mul_f32_e32 v38, v38, v38
	v_mul_f32_e32 v39, v39, v39
	v_mul_f32_e32 v32, v32, v32
	v_mul_f32_e32 v33, v33, v33
	v_mul_f32_e32 v34, v34, v34
	v_mul_f32_e32 v35, v35, v35
	v_cvt_pk_bf16_f32 v152, v36, v37
	v_cvt_pk_bf16_f32 v153, v38, v39
	v_cvt_pk_bf16_f32 v154, v32, v33
	v_cvt_pk_bf16_f32 v155, v34, v35
	buffer_store_dwordx4 v[152:155], v156, s[72:75], s2 offen offset:256
	s_mul_i32 s2, s33, 0x140
	v_max_f32_e32 v28, 0, v28
	v_max_f32_e32 v29, 0, v29
	v_max_f32_e32 v30, 0, v30
	v_max_f32_e32 v31, 0, v31
	v_max_f32_e32 v24, 0, v24
	v_max_f32_e32 v25, 0, v25
	v_max_f32_e32 v26, 0, v26
	v_max_f32_e32 v27, 0, v27
	v_mul_f32_e32 v28, v28, v28
	v_mul_f32_e32 v29, v29, v29
	v_mul_f32_e32 v30, v30, v30
	v_mul_f32_e32 v31, v31, v31
	v_mul_f32_e32 v24, v24, v24
	v_mul_f32_e32 v25, v25, v25
	v_mul_f32_e32 v26, v26, v26
	v_mul_f32_e32 v27, v27, v27
	v_cvt_pk_bf16_f32 v144, v28, v29
	v_cvt_pk_bf16_f32 v145, v30, v31
	v_cvt_pk_bf16_f32 v146, v24, v25
	v_cvt_pk_bf16_f32 v147, v26, v27
	buffer_store_dwordx4 v[144:147], v156, s[72:75], s2 offen
	v_max_f32_e32 v20, 0, v20
	v_max_f32_e32 v21, 0, v21
	v_max_f32_e32 v22, 0, v22
	v_max_f32_e32 v23, 0, v23
	v_max_f32_e32 v16, 0, v16
	v_max_f32_e32 v17, 0, v17
	v_max_f32_e32 v18, 0, v18
	v_max_f32_e32 v19, 0, v19
	v_mul_f32_e32 v20, v20, v20
	v_mul_f32_e32 v21, v21, v21
	v_mul_f32_e32 v22, v22, v22
	v_mul_f32_e32 v23, v23, v23
	v_mul_f32_e32 v16, v16, v16
	v_mul_f32_e32 v17, v17, v17
	v_mul_f32_e32 v18, v18, v18
	v_mul_f32_e32 v19, v19, v19
	v_cvt_pk_bf16_f32 v152, v20, v21
	v_cvt_pk_bf16_f32 v153, v22, v23
	v_cvt_pk_bf16_f32 v154, v16, v17
	v_cvt_pk_bf16_f32 v155, v18, v19
	buffer_store_dwordx4 v[152:155], v156, s[72:75], s2 offen offset:256
	s_mul_i32 s2, s33, 0x160
	v_max_f32_e32 v12, 0, v12
	v_max_f32_e32 v13, 0, v13
	v_max_f32_e32 v14, 0, v14
	v_max_f32_e32 v15, 0, v15
	v_max_f32_e32 v8, 0, v8
	v_max_f32_e32 v9, 0, v9
	v_max_f32_e32 v10, 0, v10
	v_max_f32_e32 v11, 0, v11
	v_mul_f32_e32 v12, v12, v12
	v_mul_f32_e32 v13, v13, v13
	v_mul_f32_e32 v14, v14, v14
	v_mul_f32_e32 v15, v15, v15
	v_mul_f32_e32 v8, v8, v8
	v_mul_f32_e32 v9, v9, v9
	v_mul_f32_e32 v10, v10, v10
	v_mul_f32_e32 v11, v11, v11
	v_cvt_pk_bf16_f32 v144, v12, v13
	v_cvt_pk_bf16_f32 v145, v14, v15
	v_cvt_pk_bf16_f32 v146, v8, v9
	v_cvt_pk_bf16_f32 v147, v10, v11
	buffer_store_dwordx4 v[144:147], v156, s[72:75], s2 offen
	v_max_f32_e32 v4, 0, v4
	v_max_f32_e32 v5, 0, v5
	v_max_f32_e32 v6, 0, v6
	v_max_f32_e32 v7, 0, v7
	v_max_f32_e32 v0, 0, v0
	v_max_f32_e32 v1, 0, v1
	v_max_f32_e32 v2, 0, v2
	v_max_f32_e32 v3, 0, v3
	v_mul_f32_e32 v4, v4, v4
	v_mul_f32_e32 v5, v5, v5
	v_mul_f32_e32 v6, v6, v6
	v_mul_f32_e32 v7, v7, v7
	v_mul_f32_e32 v0, v0, v0
	v_mul_f32_e32 v1, v1, v1
	v_mul_f32_e32 v2, v2, v2
	v_mul_f32_e32 v3, v3, v3
	v_cvt_pk_bf16_f32 v152, v4, v5
	v_cvt_pk_bf16_f32 v153, v6, v7
	v_cvt_pk_bf16_f32 v154, v0, v1
	v_cvt_pk_bf16_f32 v155, v2, v3
	buffer_store_dwordx4 v[152:155], v156, s[72:75], s2 offen offset:256
	s_branch .LBB0_509
